# v40 + row folds in the cold-load shadow + dead relu/convert work removed from the ffn1 half-tile epilogues
# baseline (speedup 1.0000x reference)
.Lh0_B_163:
	v_lshl_add_u32 v148, s39, 8, v150
	v_max_f32_e32 v124, v124, v124
	v_max_f32_e32 v120, v120, v120
	v_max_f32_e32 v125, v125, v125
	v_max_f32_e32 v121, v121, v121
	v_max_f32_e32 v126, v126, v126
	v_max_f32_e32 v127, v127, v127
	v_lshl_or_b32 v134, s38, 8, v152
	v_ashrrev_i32_e32 v149, 31, v148
	v_max_f32_e32 v124, 0, v124
	v_max_f32_e32 v120, 0, v120
	v_max_f32_e32 v125, 0, v125
	v_max_f32_e32 v121, 0, v121
	v_max_f32_e32 v126, 0, v126
	v_max_f32_e32 v122, v122, v122
	v_max_f32_e32 v127, 0, v127
	v_max_f32_e32 v123, v123, v123
	v_lshlrev_b64 v[136:137], 13, v[148:149]
	v_pk_mul_f32 v[124:125], v[124:125], v[124:125]
	v_pk_mul_f32 v[120:121], v[120:121], v[120:121]
	v_max_f32_e32 v122, 0, v122
	v_max_f32_e32 v123, 0, v123
	v_pk_mul_f32 v[126:127], v[126:127], v[126:127]
	v_ashrrev_i32_e32 v135, 31, v134
	v_pk_mul_f32 v[154:155], v[122:123], v[122:123]
	v_cvt_pk_bf16_f32 v122, v124, v125
	v_cvt_pk_bf16_f32 v123, v126, v127
	v_cvt_pk_bf16_f32 v124, v120, v121
	v_lshl_add_u64 v[126:127], s[8:9], 0, v[136:137]
	v_lshlrev_b64 v[120:121], 1, v[134:135]
	v_cvt_pk_bf16_f32 v125, v154, v155
	v_lshl_add_u64 v[126:127], v[126:127], 0, v[120:121]
	global_store_dwordx4 v[126:127], v[122:125], off
	v_max_f32_e32 v104, v104, v104
	v_max_f32_e32 v105, v105, v105
	v_max_f32_e32 v104, 0, v104
	v_max_f32_e32 v105, 0, v105
	v_max_f32_e32 v108, v108, v108
	v_max_f32_e32 v109, v109, v109
	v_or_b32_e32 v112, 16, v148
	v_pk_mul_f32 v[114:115], v[104:105], v[104:105]
	v_max_f32_e32 v105, v106, v106
	v_ashrrev_i32_e32 v113, 31, v112
	v_max_f32_e32 v108, 0, v108
	v_max_f32_e32 v109, 0, v109
	v_max_f32_e32 v104, v110, v110
	v_max_f32_e32 v106, 0, v105
	v_max_f32_e32 v105, v111, v111
	v_max_f32_e32 v107, v107, v107
	v_lshlrev_b64 v[112:113], 13, v[112:113]
	v_pk_mul_f32 v[108:109], v[108:109], v[108:109]
	v_max_f32_e32 v104, 0, v104
	v_max_f32_e32 v105, 0, v105
	v_max_f32_e32 v107, 0, v107
	v_pk_mul_f32 v[110:111], v[104:105], v[104:105]
	v_pk_mul_f32 v[116:117], v[106:107], v[106:107]
	v_cvt_pk_bf16_f32 v104, v108, v109
	v_lshl_add_u64 v[108:109], s[8:9], 0, v[112:113]
	v_cvt_pk_bf16_f32 v105, v110, v111
	v_cvt_pk_bf16_f32 v106, v114, v115
	v_cvt_pk_bf16_f32 v107, v116, v117
	v_lshl_add_u64 v[108:109], v[108:109], 0, v[120:121]
	global_store_dwordx4 v[108:109], v[104:107], off
	v_max_f32_e32 v88, v88, v88
	v_max_f32_e32 v89, v89, v89
	v_max_f32_e32 v88, 0, v88
	v_max_f32_e32 v89, 0, v89
	v_max_f32_e32 v92, v92, v92
	v_max_f32_e32 v93, v93, v93
	v_or_b32_e32 v96, 32, v148
	v_pk_mul_f32 v[98:99], v[88:89], v[88:89]
	v_max_f32_e32 v89, v90, v90
	v_ashrrev_i32_e32 v97, 31, v96
	v_max_f32_e32 v92, 0, v92
	v_max_f32_e32 v93, 0, v93
	v_max_f32_e32 v88, v94, v94
	v_max_f32_e32 v90, 0, v89
	v_max_f32_e32 v89, v95, v95
	v_max_f32_e32 v91, v91, v91
	v_lshlrev_b64 v[96:97], 13, v[96:97]
	v_pk_mul_f32 v[92:93], v[92:93], v[92:93]
	v_max_f32_e32 v88, 0, v88
	v_max_f32_e32 v89, 0, v89
	v_max_f32_e32 v91, 0, v91
	v_pk_mul_f32 v[94:95], v[88:89], v[88:89]
	v_pk_mul_f32 v[100:101], v[90:91], v[90:91]
	v_cvt_pk_bf16_f32 v88, v92, v93
	v_lshl_add_u64 v[92:93], s[8:9], 0, v[96:97]
	v_cvt_pk_bf16_f32 v89, v94, v95
	v_cvt_pk_bf16_f32 v90, v98, v99
	v_cvt_pk_bf16_f32 v91, v100, v101
	v_lshl_add_u64 v[92:93], v[92:93], 0, v[120:121]
	global_store_dwordx4 v[92:93], v[88:91], off
	v_max_f32_e32 v72, v72, v72
	v_max_f32_e32 v73, v73, v73
	v_max_f32_e32 v72, 0, v72
	v_max_f32_e32 v73, 0, v73
	v_max_f32_e32 v76, v76, v76
	v_max_f32_e32 v77, v77, v77
	v_or_b32_e32 v80, 48, v148
	v_pk_mul_f32 v[82:83], v[72:73], v[72:73]
	v_max_f32_e32 v73, v74, v74
	v_ashrrev_i32_e32 v81, 31, v80
	v_max_f32_e32 v76, 0, v76
	v_max_f32_e32 v77, 0, v77
	v_max_f32_e32 v72, v78, v78
	v_max_f32_e32 v74, 0, v73
	v_max_f32_e32 v73, v79, v79
	v_max_f32_e32 v75, v75, v75
	v_lshlrev_b64 v[80:81], 13, v[80:81]
	v_pk_mul_f32 v[76:77], v[76:77], v[76:77]
	v_max_f32_e32 v72, 0, v72
	v_max_f32_e32 v73, 0, v73
	v_max_f32_e32 v75, 0, v75
	v_pk_mul_f32 v[78:79], v[72:73], v[72:73]
	v_pk_mul_f32 v[84:85], v[74:75], v[74:75]
	v_cvt_pk_bf16_f32 v72, v76, v77
	v_lshl_add_u64 v[76:77], s[8:9], 0, v[80:81]
	v_cvt_pk_bf16_f32 v73, v78, v79
	v_cvt_pk_bf16_f32 v74, v82, v83
	v_cvt_pk_bf16_f32 v75, v84, v85
	v_lshl_add_u64 v[76:77], v[76:77], 0, v[120:121]
	global_store_dwordx4 v[76:77], v[72:75], off
	v_max_f32_e32 v56, v56, v56
	v_max_f32_e32 v57, v57, v57
	v_max_f32_e32 v56, 0, v56
	v_max_f32_e32 v57, 0, v57
	v_max_f32_e32 v60, v60, v60
	v_max_f32_e32 v61, v61, v61
	v_add_u32_e32 v64, 0x80, v148
	v_pk_mul_f32 v[66:67], v[56:57], v[56:57]
	v_max_f32_e32 v57, v58, v58
	v_ashrrev_i32_e32 v65, 31, v64
	v_max_f32_e32 v60, 0, v60
	v_max_f32_e32 v61, 0, v61
	v_max_f32_e32 v56, v62, v62
	v_max_f32_e32 v58, 0, v57
	v_max_f32_e32 v57, v63, v63
	v_max_f32_e32 v59, v59, v59
	v_lshlrev_b64 v[64:65], 13, v[64:65]
	v_pk_mul_f32 v[60:61], v[60:61], v[60:61]
	v_max_f32_e32 v56, 0, v56
	v_max_f32_e32 v57, 0, v57
	v_max_f32_e32 v59, 0, v59
	v_pk_mul_f32 v[62:63], v[56:57], v[56:57]
	v_pk_mul_f32 v[68:69], v[58:59], v[58:59]
	v_cvt_pk_bf16_f32 v56, v60, v61
	v_lshl_add_u64 v[60:61], s[8:9], 0, v[64:65]
	v_cvt_pk_bf16_f32 v57, v62, v63
	v_cvt_pk_bf16_f32 v58, v66, v67
	v_cvt_pk_bf16_f32 v59, v68, v69
	v_lshl_add_u64 v[60:61], v[60:61], 0, v[120:121]
	global_store_dwordx4 v[60:61], v[56:59], off
	v_max_f32_e32 v40, v40, v40
	v_max_f32_e32 v41, v41, v41
	v_max_f32_e32 v40, 0, v40
	v_max_f32_e32 v41, 0, v41
	v_max_f32_e32 v44, v44, v44
	v_max_f32_e32 v45, v45, v45
	v_add_u32_e32 v48, 0x90, v148
	v_pk_mul_f32 v[50:51], v[40:41], v[40:41]
	v_max_f32_e32 v41, v42, v42
	v_ashrrev_i32_e32 v49, 31, v48
	v_max_f32_e32 v44, 0, v44
	v_max_f32_e32 v45, 0, v45
	v_max_f32_e32 v40, v46, v46
	v_max_f32_e32 v42, 0, v41
	v_max_f32_e32 v41, v47, v47
	v_max_f32_e32 v43, v43, v43
	v_lshlrev_b64 v[48:49], 13, v[48:49]
	v_pk_mul_f32 v[44:45], v[44:45], v[44:45]
	v_max_f32_e32 v40, 0, v40
	v_max_f32_e32 v41, 0, v41
	v_max_f32_e32 v43, 0, v43
	v_pk_mul_f32 v[46:47], v[40:41], v[40:41]
	v_pk_mul_f32 v[52:53], v[42:43], v[42:43]
	v_cvt_pk_bf16_f32 v40, v44, v45
	v_lshl_add_u64 v[44:45], s[8:9], 0, v[48:49]
	v_cvt_pk_bf16_f32 v41, v46, v47
	v_cvt_pk_bf16_f32 v42, v50, v51
	v_cvt_pk_bf16_f32 v43, v52, v53
	v_lshl_add_u64 v[44:45], v[44:45], 0, v[120:121]
	global_store_dwordx4 v[44:45], v[40:43], off
	v_max_f32_e32 v24, v24, v24
	v_max_f32_e32 v25, v25, v25
	v_max_f32_e32 v24, 0, v24
	v_max_f32_e32 v25, 0, v25
	v_max_f32_e32 v28, v28, v28
	v_max_f32_e32 v29, v29, v29
	v_add_u32_e32 v32, 0xa0, v148
	v_pk_mul_f32 v[34:35], v[24:25], v[24:25]
	v_max_f32_e32 v25, v26, v26
	v_ashrrev_i32_e32 v33, 31, v32
	v_max_f32_e32 v28, 0, v28
	v_max_f32_e32 v29, 0, v29
	v_max_f32_e32 v24, v30, v30
	v_max_f32_e32 v26, 0, v25
	v_max_f32_e32 v25, v31, v31
	v_max_f32_e32 v27, v27, v27
	v_lshlrev_b64 v[32:33], 13, v[32:33]
	v_pk_mul_f32 v[28:29], v[28:29], v[28:29]
	v_max_f32_e32 v24, 0, v24
	v_max_f32_e32 v25, 0, v25
	v_max_f32_e32 v27, 0, v27
	v_pk_mul_f32 v[30:31], v[24:25], v[24:25]
	v_pk_mul_f32 v[36:37], v[26:27], v[26:27]
	v_cvt_pk_bf16_f32 v24, v28, v29
	v_lshl_add_u64 v[28:29], s[8:9], 0, v[32:33]
	v_cvt_pk_bf16_f32 v25, v30, v31
	v_cvt_pk_bf16_f32 v26, v34, v35
	v_cvt_pk_bf16_f32 v27, v36, v37
	v_lshl_add_u64 v[28:29], v[28:29], 0, v[120:121]
	global_store_dwordx4 v[28:29], v[24:27], off
	v_max_f32_e32 v8, v8, v8
	v_max_f32_e32 v9, v9, v9
	v_max_f32_e32 v8, 0, v8
	v_max_f32_e32 v9, 0, v9
	v_max_f32_e32 v12, v12, v12
	v_max_f32_e32 v13, v13, v13
	v_add_u32_e32 v16, 0xb0, v148
	v_pk_mul_f32 v[18:19], v[8:9], v[8:9]
	v_max_f32_e32 v9, v10, v10
	v_ashrrev_i32_e32 v17, 31, v16
	v_max_f32_e32 v12, 0, v12
	v_max_f32_e32 v13, 0, v13
	v_max_f32_e32 v8, v14, v14
	v_max_f32_e32 v10, 0, v9
	v_max_f32_e32 v9, v15, v15
	v_max_f32_e32 v11, v11, v11
	v_lshlrev_b64 v[16:17], 13, v[16:17]
	v_pk_mul_f32 v[12:13], v[12:13], v[12:13]
	v_max_f32_e32 v8, 0, v8
	v_max_f32_e32 v9, 0, v9
	v_max_f32_e32 v11, 0, v11
	v_pk_mul_f32 v[14:15], v[8:9], v[8:9]
	v_pk_mul_f32 v[20:21], v[10:11], v[10:11]
	v_cvt_pk_bf16_f32 v8, v12, v13
	v_lshl_add_u64 v[12:13], s[8:9], 0, v[16:17]
	v_cvt_pk_bf16_f32 v9, v14, v15
	v_cvt_pk_bf16_f32 v10, v18, v19
	v_cvt_pk_bf16_f32 v11, v20, v21
	v_lshl_add_u64 v[12:13], v[12:13], 0, v[120:121]
	global_store_dwordx4 v[12:13], v[8:11], off
	s_andn2_b64 vcc, exec, s[0:1]
	s_mov_b64 s[0:1], -1
	s_movk_i32 s48, 0x90
	s_cbranch_vccnz .LBB0_156
	s_andn2_b64 vcc, exec, s[4:5]
	s_cbranch_vccnz .LBB0_155
	s_barrier
	s_branch .LBB0_155

.Lh1_B_163:
	v_lshl_add_u32 v148, s39, 8, v150
	v_lshl_or_b32 v134, s38, 8, v152
	v_ashrrev_i32_e32 v149, 31, v148
	v_lshlrev_b64 v[136:137], 13, v[148:149]
	v_ashrrev_i32_e32 v135, 31, v134
	v_lshl_add_u64 v[126:127], s[8:9], 0, v[136:137]
	v_lshlrev_b64 v[120:121], 1, v[134:135]
	v_max_f32_e32 v112, v112, v112
	v_max_f32_e32 v113, v113, v113
	v_lshl_add_u64 v[126:127], v[126:127], 0, v[120:121]
	v_max_f32_e32 v112, 0, v112
	v_max_f32_e32 v113, 0, v113
	v_max_f32_e32 v116, v116, v116
	v_max_f32_e32 v117, v117, v117
	v_pk_mul_f32 v[122:123], v[112:113], v[112:113]
	v_max_f32_e32 v113, v114, v114
	v_max_f32_e32 v112, v118, v118
	v_max_f32_e32 v114, 0, v113
	v_max_f32_e32 v113, v119, v119
	v_max_f32_e32 v115, v115, v115
	v_max_f32_e32 v116, 0, v116
	v_max_f32_e32 v117, 0, v117
	v_max_f32_e32 v112, 0, v112
	v_max_f32_e32 v113, 0, v113
	v_max_f32_e32 v115, 0, v115
	v_pk_mul_f32 v[116:117], v[116:117], v[116:117]
	v_pk_mul_f32 v[118:119], v[112:113], v[112:113]
	v_pk_mul_f32 v[124:125], v[114:115], v[114:115]
	v_cvt_pk_bf16_f32 v112, v116, v117
	v_cvt_pk_bf16_f32 v113, v118, v119
	v_cvt_pk_bf16_f32 v114, v122, v123
	v_cvt_pk_bf16_f32 v115, v124, v125
	global_store_dwordx4 v[126:127], v[112:115], off offset:256
	s_nop 1
	v_or_b32_e32 v112, 16, v148
	v_ashrrev_i32_e32 v113, 31, v112
	v_lshlrev_b64 v[112:113], 13, v[112:113]
	v_lshl_add_u64 v[108:109], s[8:9], 0, v[112:113]
	v_max_f32_e32 v96, v96, v96
	v_max_f32_e32 v97, v97, v97
	v_lshl_add_u64 v[108:109], v[108:109], 0, v[120:121]
	v_max_f32_e32 v96, 0, v96
	v_max_f32_e32 v97, 0, v97
	v_max_f32_e32 v100, v100, v100
	v_max_f32_e32 v101, v101, v101
	v_pk_mul_f32 v[104:105], v[96:97], v[96:97]
	v_max_f32_e32 v97, v98, v98
	v_max_f32_e32 v96, v102, v102
	v_max_f32_e32 v98, 0, v97
	v_max_f32_e32 v97, v103, v103
	v_max_f32_e32 v99, v99, v99
	v_max_f32_e32 v100, 0, v100
	v_max_f32_e32 v101, 0, v101
	v_max_f32_e32 v96, 0, v96
	v_max_f32_e32 v97, 0, v97
	v_max_f32_e32 v99, 0, v99
	v_pk_mul_f32 v[100:101], v[100:101], v[100:101]
	v_pk_mul_f32 v[102:103], v[96:97], v[96:97]
	v_pk_mul_f32 v[106:107], v[98:99], v[98:99]
	v_cvt_pk_bf16_f32 v96, v100, v101
	v_cvt_pk_bf16_f32 v97, v102, v103
	v_cvt_pk_bf16_f32 v98, v104, v105
	v_cvt_pk_bf16_f32 v99, v106, v107
	global_store_dwordx4 v[108:109], v[96:99], off offset:256
	s_nop 1
	v_or_b32_e32 v96, 32, v148
	v_ashrrev_i32_e32 v97, 31, v96
	v_lshlrev_b64 v[96:97], 13, v[96:97]
	v_lshl_add_u64 v[92:93], s[8:9], 0, v[96:97]
	v_max_f32_e32 v80, v80, v80
	v_max_f32_e32 v81, v81, v81
	v_lshl_add_u64 v[92:93], v[92:93], 0, v[120:121]
	v_max_f32_e32 v80, 0, v80
	v_max_f32_e32 v81, 0, v81
	v_max_f32_e32 v84, v84, v84
	v_max_f32_e32 v85, v85, v85
	v_pk_mul_f32 v[88:89], v[80:81], v[80:81]
	v_max_f32_e32 v81, v82, v82
	v_max_f32_e32 v80, v86, v86
	v_max_f32_e32 v82, 0, v81
	v_max_f32_e32 v81, v87, v87
	v_max_f32_e32 v83, v83, v83
	v_max_f32_e32 v84, 0, v84
	v_max_f32_e32 v85, 0, v85
	v_max_f32_e32 v80, 0, v80
	v_max_f32_e32 v81, 0, v81
	v_max_f32_e32 v83, 0, v83
	v_pk_mul_f32 v[84:85], v[84:85], v[84:85]
	v_pk_mul_f32 v[86:87], v[80:81], v[80:81]
	v_pk_mul_f32 v[90:91], v[82:83], v[82:83]
	v_cvt_pk_bf16_f32 v80, v84, v85
	v_cvt_pk_bf16_f32 v81, v86, v87
	v_cvt_pk_bf16_f32 v82, v88, v89
	v_cvt_pk_bf16_f32 v83, v90, v91
	global_store_dwordx4 v[92:93], v[80:83], off offset:256
	s_nop 1
	v_or_b32_e32 v80, 48, v148
	v_ashrrev_i32_e32 v81, 31, v80
	v_lshlrev_b64 v[80:81], 13, v[80:81]
	v_lshl_add_u64 v[76:77], s[8:9], 0, v[80:81]
	v_max_f32_e32 v64, v64, v64
	v_max_f32_e32 v65, v65, v65
	v_lshl_add_u64 v[76:77], v[76:77], 0, v[120:121]
	v_max_f32_e32 v64, 0, v64
	v_max_f32_e32 v65, 0, v65
	v_max_f32_e32 v68, v68, v68
	v_max_f32_e32 v69, v69, v69
	v_pk_mul_f32 v[72:73], v[64:65], v[64:65]
	v_max_f32_e32 v65, v66, v66
	v_max_f32_e32 v64, v70, v70
	v_max_f32_e32 v66, 0, v65
	v_max_f32_e32 v65, v71, v71
	v_max_f32_e32 v67, v67, v67
	v_max_f32_e32 v68, 0, v68
	v_max_f32_e32 v69, 0, v69
	v_max_f32_e32 v64, 0, v64
	v_max_f32_e32 v65, 0, v65
	v_max_f32_e32 v67, 0, v67
	v_pk_mul_f32 v[68:69], v[68:69], v[68:69]
	v_pk_mul_f32 v[70:71], v[64:65], v[64:65]
	v_pk_mul_f32 v[74:75], v[66:67], v[66:67]
	v_cvt_pk_bf16_f32 v64, v68, v69
	v_cvt_pk_bf16_f32 v65, v70, v71
	v_cvt_pk_bf16_f32 v66, v72, v73
	v_cvt_pk_bf16_f32 v67, v74, v75
	global_store_dwordx4 v[76:77], v[64:67], off offset:256
	s_nop 1
	v_add_u32_e32 v64, 0x80, v148
	v_ashrrev_i32_e32 v65, 31, v64
	v_lshlrev_b64 v[64:65], 13, v[64:65]
	v_lshl_add_u64 v[60:61], s[8:9], 0, v[64:65]
	v_max_f32_e32 v48, v48, v48
	v_max_f32_e32 v49, v49, v49
	v_lshl_add_u64 v[60:61], v[60:61], 0, v[120:121]
	v_max_f32_e32 v48, 0, v48
	v_max_f32_e32 v49, 0, v49
	v_max_f32_e32 v52, v52, v52
	v_max_f32_e32 v53, v53, v53
	v_pk_mul_f32 v[56:57], v[48:49], v[48:49]
	v_max_f32_e32 v49, v50, v50
	v_max_f32_e32 v48, v54, v54
	v_max_f32_e32 v50, 0, v49
	v_max_f32_e32 v49, v55, v55
	v_max_f32_e32 v51, v51, v51
	v_max_f32_e32 v52, 0, v52
	v_max_f32_e32 v53, 0, v53
	v_max_f32_e32 v48, 0, v48
	v_max_f32_e32 v49, 0, v49
	v_max_f32_e32 v51, 0, v51
	v_pk_mul_f32 v[52:53], v[52:53], v[52:53]
	v_pk_mul_f32 v[54:55], v[48:49], v[48:49]
	v_pk_mul_f32 v[58:59], v[50:51], v[50:51]
	v_cvt_pk_bf16_f32 v48, v52, v53
	v_cvt_pk_bf16_f32 v49, v54, v55
	v_cvt_pk_bf16_f32 v50, v56, v57
	v_cvt_pk_bf16_f32 v51, v58, v59
	global_store_dwordx4 v[60:61], v[48:51], off offset:256
	s_nop 1
	v_add_u32_e32 v48, 0x90, v148
	v_ashrrev_i32_e32 v49, 31, v48
	v_lshlrev_b64 v[48:49], 13, v[48:49]
	v_lshl_add_u64 v[44:45], s[8:9], 0, v[48:49]
	v_max_f32_e32 v32, v32, v32
	v_max_f32_e32 v33, v33, v33
	v_lshl_add_u64 v[44:45], v[44:45], 0, v[120:121]
	v_max_f32_e32 v32, 0, v32
	v_max_f32_e32 v33, 0, v33
	v_max_f32_e32 v36, v36, v36
	v_max_f32_e32 v37, v37, v37
	v_pk_mul_f32 v[40:41], v[32:33], v[32:33]
	v_max_f32_e32 v33, v34, v34
	v_max_f32_e32 v32, v38, v38
	v_max_f32_e32 v34, 0, v33
	v_max_f32_e32 v33, v39, v39
	v_max_f32_e32 v35, v35, v35
	v_max_f32_e32 v36, 0, v36
	v_max_f32_e32 v37, 0, v37
	v_max_f32_e32 v32, 0, v32
	v_max_f32_e32 v33, 0, v33
	v_max_f32_e32 v35, 0, v35
	v_pk_mul_f32 v[36:37], v[36:37], v[36:37]
	v_pk_mul_f32 v[38:39], v[32:33], v[32:33]
	v_pk_mul_f32 v[42:43], v[34:35], v[34:35]
	v_cvt_pk_bf16_f32 v32, v36, v37
	v_cvt_pk_bf16_f32 v33, v38, v39
	v_cvt_pk_bf16_f32 v34, v40, v41
	v_cvt_pk_bf16_f32 v35, v42, v43
	global_store_dwordx4 v[44:45], v[32:35], off offset:256
	s_nop 1
	v_add_u32_e32 v32, 0xa0, v148
	v_ashrrev_i32_e32 v33, 31, v32
	v_lshlrev_b64 v[32:33], 13, v[32:33]
	v_lshl_add_u64 v[28:29], s[8:9], 0, v[32:33]
	v_max_f32_e32 v16, v16, v16
	v_max_f32_e32 v17, v17, v17
	v_lshl_add_u64 v[28:29], v[28:29], 0, v[120:121]
	v_max_f32_e32 v16, 0, v16
	v_max_f32_e32 v17, 0, v17
	v_max_f32_e32 v20, v20, v20
	v_max_f32_e32 v21, v21, v21
	v_pk_mul_f32 v[24:25], v[16:17], v[16:17]
	v_max_f32_e32 v17, v18, v18
	v_max_f32_e32 v16, v22, v22
	v_max_f32_e32 v18, 0, v17
	v_max_f32_e32 v17, v23, v23
	v_max_f32_e32 v19, v19, v19
	v_max_f32_e32 v20, 0, v20
	v_max_f32_e32 v21, 0, v21
	v_max_f32_e32 v16, 0, v16
	v_max_f32_e32 v17, 0, v17
	v_max_f32_e32 v19, 0, v19
	v_pk_mul_f32 v[20:21], v[20:21], v[20:21]
	v_pk_mul_f32 v[22:23], v[16:17], v[16:17]
	v_pk_mul_f32 v[26:27], v[18:19], v[18:19]
	v_cvt_pk_bf16_f32 v16, v20, v21
	v_cvt_pk_bf16_f32 v17, v22, v23
	v_cvt_pk_bf16_f32 v18, v24, v25
	v_cvt_pk_bf16_f32 v19, v26, v27
	global_store_dwordx4 v[28:29], v[16:19], off offset:256
	s_nop 1
	v_add_u32_e32 v16, 0xb0, v148
	v_ashrrev_i32_e32 v17, 31, v16
	v_lshlrev_b64 v[16:17], 13, v[16:17]
	v_lshl_add_u64 v[12:13], s[8:9], 0, v[16:17]
	v_max_f32_e32 v0, v0, v0
	v_max_f32_e32 v1, v1, v1
	v_lshl_add_u64 v[12:13], v[12:13], 0, v[120:121]
	v_max_f32_e32 v0, 0, v0
	v_max_f32_e32 v1, 0, v1
	v_max_f32_e32 v4, v4, v4
	v_max_f32_e32 v5, v5, v5
	v_pk_mul_f32 v[8:9], v[0:1], v[0:1]
	v_max_f32_e32 v1, v2, v2
	v_max_f32_e32 v0, v6, v6
	v_max_f32_e32 v2, 0, v1
	v_max_f32_e32 v1, v7, v7
	v_max_f32_e32 v3, v3, v3
	v_max_f32_e32 v4, 0, v4
	v_max_f32_e32 v5, 0, v5
	v_max_f32_e32 v0, 0, v0
	v_max_f32_e32 v1, 0, v1
	v_max_f32_e32 v3, 0, v3
	v_pk_mul_f32 v[4:5], v[4:5], v[4:5]
	v_pk_mul_f32 v[6:7], v[0:1], v[0:1]
	v_pk_mul_f32 v[10:11], v[2:3], v[2:3]
	v_cvt_pk_bf16_f32 v0, v4, v5
	v_cvt_pk_bf16_f32 v1, v6, v7
	v_cvt_pk_bf16_f32 v2, v8, v9
	v_cvt_pk_bf16_f32 v3, v10, v11
	s_andn2_b64 vcc, exec, s[0:1]
	s_mov_b64 s[0:1], -1
	s_movk_i32 s48, 0x90
	global_store_dwordx4 v[12:13], v[0:3], off offset:256
	s_cbranch_vccnz .LBB0_156
	s_andn2_b64 vcc, exec, s[4:5]
	s_cbranch_vccnz .LBB0_155
	s_barrier
	s_branch .LBB0_155
